# attention: odd hardware wave slots start the item 2560 cycles late (was 1280) at raised priority
# baseline (speedup 1.0000x reference)
.LBB0_344:
	s_getreg_b32 s98, hwreg(HW_REG_HW_ID, 0, 4)
	s_bitcmp1_b32 s98, 0
	s_cbranch_scc0 .Lattn_nosleep
	s_sleep 40
	s_setprio 1
